# grid barrier: each arriving workgroup issues an un-waited buffer_wbl2 so the L2 write-back starts before the last arrival
# baseline (speedup 1.0000x reference)
.LBB0_1179:
	s_mov_b64 s[4:5], exec
	v_mbcnt_lo_u32_b32 v0, s4, 0
	v_mbcnt_hi_u32_b32 v0, s5, v0
	v_cmp_eq_u32_e32 vcc, 0, v0
	s_and_saveexec_b64 s[2:3], vcc
	s_cbranch_execz .LBB0_1181
	s_bcnt1_i32_b64 s4, s[4:5]
	v_mov_b32_e32 v4, s4
	v_readlane_b32 s4, v252, 7
	v_readlane_b32 s5, v252, 8
	s_nop 4
	global_atomic_add v4, v1, v4, s[4:5] sc0
	buffer_wbl2 sc1
.LBB0_1181:
	s_or_b64 exec, exec, s[2:3]
	v_cvt_f32_u32_e32 v5, v3
	s_waitcnt vmcnt(1)
	v_readfirstlane_b32 s2, v4
	v_sub_u32_e32 v4, 0, v3
	v_rcp_iflag_f32_e32 v5, v5
	v_add_u32_e32 v6, s2, v0
	v_mul_f32_e32 v5, 0x4f7ffffe, v5
	v_cvt_u32_f32_e32 v5, v5
	v_mul_lo_u32 v0, v4, v5
	v_mul_hi_u32 v0, v5, v0
	v_add_u32_e32 v0, v5, v0
	v_mul_hi_u32 v0, v6, v0
	v_mul_lo_u32 v4, v0, v3
	v_sub_u32_e32 v4, v6, v4
	v_add_u32_e32 v5, 1, v0
	v_cmp_ge_u32_e32 vcc, v4, v3
	s_nop 1
	v_cndmask_b32_e32 v0, v0, v5, vcc
	v_sub_u32_e32 v5, v4, v3
	v_cndmask_b32_e32 v4, v4, v5, vcc
	v_add_u32_e32 v5, 1, v0
	v_cmp_ge_u32_e32 vcc, v4, v3
	v_add_u32_e32 v4, 1, v6
	s_nop 0
	v_cndmask_b32_e32 v0, v0, v5, vcc
	v_mul_lo_u32 v5, v3, v0
	v_add_u32_e32 v3, v5, v3
	v_cmp_ne_u32_e32 vcc, v4, v3
	s_and_saveexec_b64 s[2:3], vcc
	s_xor_b64 s[2:3], exec, s[2:3]
	s_cbranch_execz .LBB0_1195
	v_readlane_b32 s4, v252, 9
	v_readlane_b32 s5, v252, 10
	s_waitcnt lgkmcnt(0)
	s_nop 3
	global_load_dword v2, v1, s[4:5] sc1
	s_waitcnt vmcnt(0)
	v_cmp_eq_u32_e32 vcc, v2, v0
	s_and_saveexec_b64 s[4:5], vcc
	s_cbranch_execz .LBB0_1194
	s_mov_b32 s16, 1
	s_mov_b64 s[6:7], 0
	s_branch .LBB0_1185
